# P0 transposes: all 32 row-pair loads of an item issued up front, counted vmcnt per LDS write pair (was 4 drained batches of 8)
# baseline (speedup 1.0000x reference)
.LBB0_29:
	v_mov_b32_e32 v51, 0
	v_mov_b32_e32 v50, v18
	v_lshl_add_u64 v[52:53], v[50:51], 2, v[16:17]
	global_load_dword v108, v[52:53], off nt
	v_add_u32_e32 v50, 0x2000, v18
	v_lshl_add_u64 v[52:53], v[50:51], 2, v[16:17]
	global_load_dword v109, v[52:53], off nt
	v_add_u32_e32 v50, 0x4000, v18
	v_lshl_add_u64 v[52:53], v[50:51], 2, v[16:17]
	global_load_dword v110, v[52:53], off nt
	v_add_u32_e32 v50, 0x6000, v18
	v_lshl_add_u64 v[52:53], v[50:51], 2, v[16:17]
	global_load_dword v111, v[52:53], off nt
	v_add_u32_e32 v50, 0x8000, v18
	v_lshl_add_u64 v[52:53], v[50:51], 2, v[16:17]
	global_load_dword v112, v[52:53], off nt
	v_add_u32_e32 v50, 0xa000, v18
	v_lshl_add_u64 v[52:53], v[50:51], 2, v[16:17]
	global_load_dword v113, v[52:53], off nt
	v_add_u32_e32 v50, 0xc000, v18
	v_lshl_add_u64 v[52:53], v[50:51], 2, v[16:17]
	global_load_dword v114, v[52:53], off nt
	v_add_u32_e32 v50, 0xe000, v18
	v_lshl_add_u64 v[52:53], v[50:51], 2, v[16:17]
	global_load_dword v115, v[52:53], off nt
	v_add_u32_e32 v50, 0x10000, v18
	v_lshl_add_u64 v[52:53], v[50:51], 2, v[16:17]
	global_load_dword v116, v[52:53], off nt
	v_add_u32_e32 v50, 0x12000, v18
	v_lshl_add_u64 v[52:53], v[50:51], 2, v[16:17]
	global_load_dword v117, v[52:53], off nt
	v_add_u32_e32 v50, 0x14000, v18
	v_lshl_add_u64 v[52:53], v[50:51], 2, v[16:17]
	global_load_dword v118, v[52:53], off nt
	v_add_u32_e32 v50, 0x16000, v18
	v_lshl_add_u64 v[52:53], v[50:51], 2, v[16:17]
	global_load_dword v119, v[52:53], off nt
	v_add_u32_e32 v50, 0x18000, v18
	v_lshl_add_u64 v[52:53], v[50:51], 2, v[16:17]
	global_load_dword v120, v[52:53], off nt
	v_add_u32_e32 v50, 0x1a000, v18
	v_lshl_add_u64 v[52:53], v[50:51], 2, v[16:17]
	global_load_dword v121, v[52:53], off nt
	v_add_u32_e32 v50, 0x1c000, v18
	v_lshl_add_u64 v[52:53], v[50:51], 2, v[16:17]
	global_load_dword v122, v[52:53], off nt
	v_add_u32_e32 v50, 0x1e000, v18
	v_lshl_add_u64 v[52:53], v[50:51], 2, v[16:17]
	global_load_dword v123, v[52:53], off nt
	v_add_u32_e32 v50, 0x20000, v18
	v_lshl_add_u64 v[52:53], v[50:51], 2, v[16:17]
	global_load_dword v124, v[52:53], off nt
	v_add_u32_e32 v50, 0x22000, v18
	v_lshl_add_u64 v[52:53], v[50:51], 2, v[16:17]
	global_load_dword v125, v[52:53], off nt
	v_add_u32_e32 v50, 0x24000, v18
	v_lshl_add_u64 v[52:53], v[50:51], 2, v[16:17]
	global_load_dword v126, v[52:53], off nt
	v_add_u32_e32 v50, 0x26000, v18
	v_lshl_add_u64 v[52:53], v[50:51], 2, v[16:17]
	global_load_dword v127, v[52:53], off nt
	v_add_u32_e32 v50, 0x28000, v18
	v_lshl_add_u64 v[52:53], v[50:51], 2, v[16:17]
	global_load_dword v128, v[52:53], off nt
	v_add_u32_e32 v50, 0x2a000, v18
	v_lshl_add_u64 v[52:53], v[50:51], 2, v[16:17]
	global_load_dword v129, v[52:53], off nt
	v_add_u32_e32 v50, 0x2c000, v18
	v_lshl_add_u64 v[52:53], v[50:51], 2, v[16:17]
	global_load_dword v130, v[52:53], off nt
	v_add_u32_e32 v50, 0x2e000, v18
	v_lshl_add_u64 v[52:53], v[50:51], 2, v[16:17]
	global_load_dword v131, v[52:53], off nt
	v_add_u32_e32 v50, 0x30000, v18
	v_lshl_add_u64 v[52:53], v[50:51], 2, v[16:17]
	global_load_dword v132, v[52:53], off nt
	v_add_u32_e32 v50, 0x32000, v18
	v_lshl_add_u64 v[52:53], v[50:51], 2, v[16:17]
	global_load_dword v133, v[52:53], off nt
	v_add_u32_e32 v50, 0x34000, v18
	v_lshl_add_u64 v[52:53], v[50:51], 2, v[16:17]
	global_load_dword v134, v[52:53], off nt
	v_add_u32_e32 v50, 0x36000, v18
	v_lshl_add_u64 v[52:53], v[50:51], 2, v[16:17]
	global_load_dword v135, v[52:53], off nt
	v_add_u32_e32 v50, 0x38000, v18
	v_lshl_add_u64 v[52:53], v[50:51], 2, v[16:17]
	global_load_dword v136, v[52:53], off nt
	v_add_u32_e32 v50, 0x3a000, v18
	v_lshl_add_u64 v[52:53], v[50:51], 2, v[16:17]
	global_load_dword v137, v[52:53], off nt
	v_add_u32_e32 v50, 0x3c000, v18
	v_lshl_add_u64 v[52:53], v[50:51], 2, v[16:17]
	global_load_dword v138, v[52:53], off nt
	v_add_u32_e32 v50, 0x3e000, v18
	v_lshl_add_u64 v[52:53], v[50:51], 2, v[16:17]
	global_load_dword v139, v[52:53], off nt
	v_mov_b32_e32 v140, v39
	v_add_u32_e32 v141, 0x400, v140
	s_waitcnt vmcnt(30)
	ds_write2_b32 v140, v108, v109 offset1:66
	s_waitcnt vmcnt(28)
	ds_write2_b32 v140, v110, v111 offset0:132 offset1:198
	s_waitcnt vmcnt(26)
	ds_write2_b32 v141, v112, v113 offset0:8 offset1:74
	s_waitcnt vmcnt(24)
	ds_write2_b32 v141, v114, v115 offset0:140 offset1:206
	v_add_u32_e32 v140, 0x840, v39
	v_add_u32_e32 v141, 0x400, v140
	s_waitcnt vmcnt(22)
	ds_write2_b32 v140, v116, v117 offset1:66
	s_waitcnt vmcnt(20)
	ds_write2_b32 v140, v118, v119 offset0:132 offset1:198
	s_waitcnt vmcnt(18)
	ds_write2_b32 v141, v120, v121 offset0:8 offset1:74
	s_waitcnt vmcnt(16)
	ds_write2_b32 v141, v122, v123 offset0:140 offset1:206
	v_add_u32_e32 v140, 0x1080, v39
	v_add_u32_e32 v141, 0x400, v140
	s_waitcnt vmcnt(14)
	ds_write2_b32 v140, v124, v125 offset1:66
	s_waitcnt vmcnt(12)
	ds_write2_b32 v140, v126, v127 offset0:132 offset1:198
	s_waitcnt vmcnt(10)
	ds_write2_b32 v141, v128, v129 offset0:8 offset1:74
	s_waitcnt vmcnt(8)
	ds_write2_b32 v141, v130, v131 offset0:140 offset1:206
	v_add_u32_e32 v140, 0x18c0, v39
	v_add_u32_e32 v141, 0x400, v140
	s_waitcnt vmcnt(6)
	ds_write2_b32 v140, v132, v133 offset1:66
	s_waitcnt vmcnt(4)
	ds_write2_b32 v140, v134, v135 offset0:132 offset1:198
	s_waitcnt vmcnt(2)
	ds_write2_b32 v141, v136, v137 offset0:8 offset1:74
	s_waitcnt vmcnt(0)
	ds_write2_b32 v141, v138, v139 offset0:140 offset1:206
	s_waitcnt lgkmcnt(0)
	ds_read2_b32 v[16:17], v34 offset1:8
	ds_read2_b32 v[18:19], v34 offset0:33 offset1:41
	ds_read2_b32 v[20:21], v34 offset0:66 offset1:74
	ds_read2_b32 v[22:23], v34 offset0:99 offset1:107
	v_mov_b32_e32 v26, v1
	s_waitcnt lgkmcnt(3)
	v_mul_f32_e32 v0, 0x43800000, v16
	s_waitcnt lgkmcnt(2)
	v_mul_f32_e32 v16, 0x43800000, v18
	v_med3_f32 v0, v0, s15, v48
	v_med3_f32 v16, v16, s15, v48
	v_cvt_pk_fp8_f32 v26, v0, v16
	ds_read2_b32 v[28:29], v34 offset0:132 offset1:140
	ds_read2_b32 v[30:31], v34 offset0:165 offset1:173
	ds_read2_b32 v[50:51], v34 offset0:198 offset1:206
	s_waitcnt lgkmcnt(4)
	v_mul_f32_e32 v18, 0x43800000, v20
	s_waitcnt lgkmcnt(3)
	v_mul_f32_e32 v20, 0x43800000, v22
	v_med3_f32 v0, v18, s15, v48
	v_med3_f32 v16, v20, s15, v48
	ds_read2_b32 v[52:53], v34 offset0:231 offset1:239
	v_cvt_pk_fp8_f32 v26, v0, v16 op_sel:[0,0,1]
	s_waitcnt lgkmcnt(3)
	v_mul_f32_e32 v0, 0x43800000, v28
	s_waitcnt lgkmcnt(2)
	v_mul_f32_e32 v16, 0x43800000, v30
	v_med3_f32 v0, v0, s15, v48
	v_med3_f32 v16, v16, s15, v48
	v_mov_b32_e32 v27, v1
	v_cvt_pk_fp8_f32 v27, v0, v16
	s_add_i32 s4, s22, 0xffff8000
	s_waitcnt lgkmcnt(1)
	v_mul_f32_e32 v18, 0x43800000, v50
	s_waitcnt lgkmcnt(0)
	v_mul_f32_e32 v0, 0x43800000, v52
	s_lshr_b32 s4, s4, 1
	v_med3_f32 v16, v18, s15, v48
	v_med3_f32 v0, v0, s15, v48
	s_and_b32 s4, s4, 0x7fffffc0
	v_cvt_pk_fp8_f32 v27, v16, v0 op_sel:[0,0,1]
	v_or_b32_e32 v0, s6, v33
	v_lshl_add_u64 v[24:25], v[8:9], 0, s[4:5]
	v_lshlrev_b32_e32 v0, 12, v0
	v_lshl_add_u64 v[54:55], v[24:25], 0, v[0:1]
	v_mul_f32_e32 v0, 0x43800000, v17
	v_mul_f32_e32 v16, 0x43800000, v19
	v_med3_f32 v0, v0, s15, v48
	v_med3_f32 v18, v16, s15, v48
	v_mov_b32_e32 v16, v1
	v_cvt_pk_fp8_f32 v16, v0, v18
	v_mul_f32_e32 v17, 0x43800000, v21
	v_mul_f32_e32 v0, 0x43800000, v23
	v_med3_f32 v17, v17, s15, v48
	v_med3_f32 v0, v0, s15, v48
	v_cvt_pk_fp8_f32 v16, v17, v0 op_sel:[0,0,1]
	v_mul_f32_e32 v0, 0x43800000, v29
	v_mul_f32_e32 v17, 0x43800000, v31
	v_med3_f32 v0, v0, s15, v48
	v_med3_f32 v19, v17, s15, v48
	v_mov_b32_e32 v17, v1
	v_cvt_pk_fp8_f32 v17, v0, v19
	v_mul_f32_e32 v18, 0x43800000, v51
	v_mul_f32_e32 v0, 0x43800000, v53
	v_med3_f32 v18, v18, s15, v48
	v_med3_f32 v0, v0, s15, v48
	global_store_dwordx2 v[54:55], v[26:27], off
	v_cvt_pk_fp8_f32 v17, v18, v0 op_sel:[0,0,1]
	v_or_b32_e32 v0, s6, v35
	ds_read2_b32 v[20:21], v34 offset0:16 offset1:24
	ds_read2_b32 v[22:23], v34 offset0:49 offset1:57
	ds_read2_b32 v[26:27], v34 offset0:82 offset1:90
	ds_read2_b32 v[28:29], v34 offset0:115 offset1:123
	v_lshlrev_b32_e32 v0, 12, v0
	v_lshl_add_u64 v[18:19], v[24:25], 0, v[0:1]
	global_store_dwordx2 v[18:19], v[16:17], off
	s_waitcnt lgkmcnt(3)
	v_mul_f32_e32 v0, 0x43800000, v20
	s_waitcnt lgkmcnt(2)
	v_mul_f32_e32 v16, 0x43800000, v22
	v_med3_f32 v0, v0, s15, v48
	v_med3_f32 v18, v16, s15, v48
	v_mov_b32_e32 v16, v1
	v_cvt_pk_fp8_f32 v16, v0, v18
	ds_read2_b32 v[18:19], v34 offset0:148 offset1:156
	ds_read2_b32 v[30:31], v34 offset0:181 offset1:189
	ds_read2_b32 v[50:51], v34 offset0:214 offset1:222
	s_waitcnt lgkmcnt(4)
	v_mul_f32_e32 v17, 0x43800000, v26
	s_waitcnt lgkmcnt(3)
	v_mul_f32_e32 v20, 0x43800000, v28
	v_med3_f32 v0, v17, s15, v48
	v_med3_f32 v17, v20, s15, v48
	ds_read2_b32 v[52:53], v34 offset0:247 offset1:255
	v_cvt_pk_fp8_f32 v16, v0, v17 op_sel:[0,0,1]
	s_waitcnt lgkmcnt(3)
	v_mul_f32_e32 v0, 0x43800000, v18
	s_waitcnt lgkmcnt(2)
	v_mul_f32_e32 v17, 0x43800000, v30
	v_med3_f32 v0, v0, s15, v48
	v_med3_f32 v20, v17, s15, v48
	v_mov_b32_e32 v17, v1
	v_cvt_pk_fp8_f32 v17, v0, v20
	s_waitcnt lgkmcnt(1)
	v_mul_f32_e32 v18, 0x43800000, v50
	s_waitcnt lgkmcnt(0)
	v_mul_f32_e32 v0, 0x43800000, v52
	v_med3_f32 v18, v18, s15, v48
	v_med3_f32 v0, v0, s15, v48
	v_cvt_pk_fp8_f32 v17, v18, v0 op_sel:[0,0,1]
	v_or_b32_e32 v0, s6, v36
	v_lshlrev_b32_e32 v0, 12, v0
	v_lshl_add_u64 v[54:55], v[24:25], 0, v[0:1]
	global_store_dwordx2 v[54:55], v[16:17], off
	v_mul_f32_e32 v0, 0x43800000, v21
	v_mul_f32_e32 v16, 0x43800000, v23
	v_med3_f32 v0, v0, s15, v48
	v_med3_f32 v18, v16, s15, v48
	v_mov_b32_e32 v16, v1
	v_cvt_pk_fp8_f32 v16, v0, v18
	v_mul_f32_e32 v17, 0x43800000, v27
	v_mul_f32_e32 v0, 0x43800000, v29
	v_med3_f32 v17, v17, s15, v48
	v_med3_f32 v0, v0, s15, v48
	v_cvt_pk_fp8_f32 v16, v17, v0 op_sel:[0,0,1]
	v_mul_f32_e32 v0, 0x43800000, v19
	v_mul_f32_e32 v17, 0x43800000, v31
	v_med3_f32 v0, v0, s15, v48
	v_med3_f32 v19, v17, s15, v48
	v_mov_b32_e32 v17, v1
	v_cvt_pk_fp8_f32 v17, v0, v19
	v_mul_f32_e32 v18, 0x43800000, v51
	v_mul_f32_e32 v0, 0x43800000, v53
	v_med3_f32 v18, v18, s15, v48
	v_med3_f32 v0, v0, s15, v48
	v_cvt_pk_fp8_f32 v17, v18, v0 op_sel:[0,0,1]
	v_or_b32_e32 v0, s6, v37
	v_lshlrev_b32_e32 v0, 12, v0
	v_lshl_add_u64 v[18:19], v[24:25], 0, v[0:1]
	global_store_dwordx2 v[18:19], v[16:17], off
	s_waitcnt lgkmcnt(0)

.LBB0_36:
	v_lshl_add_u64 v[50:51], v[16:17], 0, s[6:7]
	v_lshl_add_u64 v[52:53], v[22:23], 0, s[6:7]
	v_lshl_add_u64 v[54:55], v[30:31], 0, s[6:7]
	v_lshl_add_u64 v[56:57], v[28:29], 0, s[6:7]
	v_lshl_add_u64 v[58:59], v[26:27], 0, s[6:7]
	v_lshl_add_u64 v[60:61], v[24:25], 0, s[6:7]
	v_lshl_add_u64 v[62:63], v[20:21], 0, s[6:7]
	v_lshl_add_u64 v[64:65], v[18:19], 0, s[6:7]
	global_load_dword v108, v[50:51], off nt
	global_load_dword v109, v[52:53], off nt
	global_load_dword v110, v[54:55], off nt
	global_load_dword v111, v[56:57], off nt
	global_load_dword v112, v[58:59], off nt
	global_load_dword v113, v[60:61], off nt
	global_load_dword v114, v[62:63], off nt
	global_load_dword v115, v[64:65], off nt
	s_add_u32 s6, s6, 0xf2800
	s_addc_u32 s7, s7, 0
	v_lshl_add_u64 v[50:51], v[16:17], 0, s[6:7]
	v_lshl_add_u64 v[52:53], v[22:23], 0, s[6:7]
	v_lshl_add_u64 v[54:55], v[30:31], 0, s[6:7]
	v_lshl_add_u64 v[56:57], v[28:29], 0, s[6:7]
	v_lshl_add_u64 v[58:59], v[26:27], 0, s[6:7]
	v_lshl_add_u64 v[60:61], v[24:25], 0, s[6:7]
	v_lshl_add_u64 v[62:63], v[20:21], 0, s[6:7]
	v_lshl_add_u64 v[64:65], v[18:19], 0, s[6:7]
	global_load_dword v116, v[50:51], off nt
	global_load_dword v117, v[52:53], off nt
	global_load_dword v118, v[54:55], off nt
	global_load_dword v119, v[56:57], off nt
	global_load_dword v120, v[58:59], off nt
	global_load_dword v121, v[60:61], off nt
	global_load_dword v122, v[62:63], off nt
	global_load_dword v123, v[64:65], off nt
	s_add_u32 s6, s6, 0xf2800
	s_addc_u32 s7, s7, 0
	v_lshl_add_u64 v[50:51], v[16:17], 0, s[6:7]
	v_lshl_add_u64 v[52:53], v[22:23], 0, s[6:7]
	v_lshl_add_u64 v[54:55], v[30:31], 0, s[6:7]
	v_lshl_add_u64 v[56:57], v[28:29], 0, s[6:7]
	v_lshl_add_u64 v[58:59], v[26:27], 0, s[6:7]
	v_lshl_add_u64 v[60:61], v[24:25], 0, s[6:7]
	v_lshl_add_u64 v[62:63], v[20:21], 0, s[6:7]
	v_lshl_add_u64 v[64:65], v[18:19], 0, s[6:7]
	global_load_dword v124, v[50:51], off nt
	global_load_dword v125, v[52:53], off nt
	global_load_dword v126, v[54:55], off nt
	global_load_dword v127, v[56:57], off nt
	global_load_dword v128, v[58:59], off nt
	global_load_dword v129, v[60:61], off nt
	global_load_dword v130, v[62:63], off nt
	global_load_dword v131, v[64:65], off nt
	s_add_u32 s6, s6, 0xf2800
	s_addc_u32 s7, s7, 0
	v_lshl_add_u64 v[50:51], v[16:17], 0, s[6:7]
	v_lshl_add_u64 v[52:53], v[22:23], 0, s[6:7]
	v_lshl_add_u64 v[54:55], v[30:31], 0, s[6:7]
	v_lshl_add_u64 v[56:57], v[28:29], 0, s[6:7]
	v_lshl_add_u64 v[58:59], v[26:27], 0, s[6:7]
	v_lshl_add_u64 v[60:61], v[24:25], 0, s[6:7]
	v_lshl_add_u64 v[62:63], v[20:21], 0, s[6:7]
	v_lshl_add_u64 v[64:65], v[18:19], 0, s[6:7]
	global_load_dword v132, v[50:51], off nt
	global_load_dword v133, v[52:53], off nt
	global_load_dword v134, v[54:55], off nt
	global_load_dword v135, v[56:57], off nt
	global_load_dword v136, v[58:59], off nt
	global_load_dword v137, v[60:61], off nt
	global_load_dword v138, v[62:63], off nt
	global_load_dword v139, v[64:65], off nt
	s_add_u32 s6, s6, 0xf2800
	s_addc_u32 s7, s7, 0
	v_mov_b32_e32 v140, v39
	v_add_u32_e32 v141, 0x400, v140
	s_waitcnt vmcnt(30)
	ds_write2_b32 v140, v108, v109 offset1:66
	s_waitcnt vmcnt(28)
	ds_write2_b32 v140, v110, v111 offset0:132 offset1:198
	s_waitcnt vmcnt(26)
	ds_write2_b32 v141, v112, v113 offset0:8 offset1:74
	s_waitcnt vmcnt(24)
	ds_write2_b32 v141, v114, v115 offset0:140 offset1:206
	v_add_u32_e32 v140, 0x840, v39
	v_add_u32_e32 v141, 0x400, v140
	s_waitcnt vmcnt(22)
	ds_write2_b32 v140, v116, v117 offset1:66
	s_waitcnt vmcnt(20)
	ds_write2_b32 v140, v118, v119 offset0:132 offset1:198
	s_waitcnt vmcnt(18)
	ds_write2_b32 v141, v120, v121 offset0:8 offset1:74
	s_waitcnt vmcnt(16)
	ds_write2_b32 v141, v122, v123 offset0:140 offset1:206
	v_add_u32_e32 v140, 0x1080, v39
	v_add_u32_e32 v141, 0x400, v140
	s_waitcnt vmcnt(14)
	ds_write2_b32 v140, v124, v125 offset1:66
	s_waitcnt vmcnt(12)
	ds_write2_b32 v140, v126, v127 offset0:132 offset1:198
	s_waitcnt vmcnt(10)
	ds_write2_b32 v141, v128, v129 offset0:8 offset1:74
	s_waitcnt vmcnt(8)
	ds_write2_b32 v141, v130, v131 offset0:140 offset1:206
	v_add_u32_e32 v140, 0x18c0, v39
	v_add_u32_e32 v141, 0x400, v140
	s_waitcnt vmcnt(6)
	ds_write2_b32 v140, v132, v133 offset1:66
	s_waitcnt vmcnt(4)
	ds_write2_b32 v140, v134, v135 offset0:132 offset1:198
	s_waitcnt vmcnt(2)
	ds_write2_b32 v141, v136, v137 offset0:8 offset1:74
	s_waitcnt vmcnt(0)
	ds_write2_b32 v141, v138, v139 offset0:140 offset1:206
	s_waitcnt lgkmcnt(0)
	ds_read2_b32 v[20:21], v34 offset0:33 offset1:41
	ds_read2_b32 v[22:23], v34 offset1:8
	ds_read2_b32 v[24:25], v34 offset0:66 offset1:74
	ds_read2_b32 v[26:27], v34 offset0:99 offset1:107
	ds_read2_b32 v[28:29], v34 offset0:132 offset1:140
	ds_read2_b32 v[30:31], v34 offset0:165 offset1:173
	ds_read2_b32 v[50:51], v34 offset0:198 offset1:206
	ds_read2_b32 v[52:53], v34 offset0:231 offset1:239
	s_lshl_b32 s4, s10, 1
	v_or_b32_e32 v0, s23, v33
	v_lshl_add_u64 v[54:55], v[10:11], 0, s[4:5]
	v_lshlrev_b32_e32 v0, 13, v0
	s_waitcnt lgkmcnt(6)
	v_cvt_pk_f16_f32 v16, v22, v20
	s_waitcnt lgkmcnt(4)
	v_cvt_pk_f16_f32 v17, v24, v26
	s_waitcnt lgkmcnt(2)
	v_cvt_pk_f16_f32 v18, v28, v30
	s_waitcnt lgkmcnt(0)
	v_cvt_pk_f16_f32 v19, v50, v52
	v_lshl_add_u64 v[56:57], v[54:55], 0, v[0:1]
	global_store_dwordx4 v[56:57], v[16:19], off
	v_or_b32_e32 v0, s23, v35
	v_lshlrev_b32_e32 v0, 13, v0
	v_cvt_pk_f16_f32 v16, v23, v21
	v_cvt_pk_f16_f32 v17, v25, v27
	v_cvt_pk_f16_f32 v18, v29, v31
	v_cvt_pk_f16_f32 v19, v51, v53
	ds_read2_b32 v[22:23], v34 offset0:49 offset1:57
	ds_read2_b32 v[24:25], v34 offset0:16 offset1:24
	ds_read2_b32 v[26:27], v34 offset0:82 offset1:90
	ds_read2_b32 v[28:29], v34 offset0:115 offset1:123
	ds_read2_b32 v[30:31], v34 offset0:148 offset1:156
	ds_read2_b32 v[50:51], v34 offset0:181 offset1:189
	ds_read2_b32 v[52:53], v34 offset0:214 offset1:222
	ds_read2_b32 v[56:57], v34 offset0:247 offset1:255
	v_lshl_add_u64 v[20:21], v[54:55], 0, v[0:1]
	v_or_b32_e32 v0, s23, v36
	v_lshlrev_b32_e32 v0, 13, v0
	global_store_dwordx4 v[20:21], v[16:19], off
	v_lshl_add_u64 v[20:21], v[54:55], 0, v[0:1]
	v_or_b32_e32 v0, s23, v37
	s_waitcnt lgkmcnt(6)
	v_cvt_pk_f16_f32 v16, v24, v22
	s_waitcnt lgkmcnt(4)
	v_cvt_pk_f16_f32 v17, v26, v28
	s_waitcnt lgkmcnt(2)
	v_cvt_pk_f16_f32 v18, v30, v50
	s_waitcnt lgkmcnt(0)
	v_cvt_pk_f16_f32 v19, v52, v56
	v_lshlrev_b32_e32 v0, 13, v0
	global_store_dwordx4 v[20:21], v[16:19], off
	v_lshl_add_u64 v[20:21], v[54:55], 0, v[0:1]
	s_mov_b64 s[6:7], 0
	v_cvt_pk_f16_f32 v16, v25, v23
	v_cvt_pk_f16_f32 v17, v27, v29
	v_cvt_pk_f16_f32 v18, v31, v51
	v_cvt_pk_f16_f32 v19, v53, v57
	global_store_dwordx4 v[20:21], v[16:19], off
	s_waitcnt lgkmcnt(0)

.LBB0_43:
	v_lshl_add_u64 v[50:51], v[16:17], 0, s[6:7]
	v_lshl_add_u64 v[52:53], v[22:23], 0, s[6:7]
	v_lshl_add_u64 v[54:55], v[30:31], 0, s[6:7]
	v_lshl_add_u64 v[56:57], v[28:29], 0, s[6:7]
	v_lshl_add_u64 v[58:59], v[26:27], 0, s[6:7]
	v_lshl_add_u64 v[60:61], v[24:25], 0, s[6:7]
	v_lshl_add_u64 v[62:63], v[20:21], 0, s[6:7]
	v_lshl_add_u64 v[64:65], v[18:19], 0, s[6:7]
	global_load_dword v108, v[50:51], off nt
	global_load_dword v109, v[52:53], off nt
	global_load_dword v110, v[54:55], off nt
	global_load_dword v111, v[56:57], off nt
	global_load_dword v112, v[58:59], off nt
	global_load_dword v113, v[60:61], off nt
	global_load_dword v114, v[62:63], off nt
	global_load_dword v115, v[64:65], off nt
	s_add_u32 s6, s6, 0xf2800
	s_addc_u32 s7, s7, 0
	v_lshl_add_u64 v[50:51], v[16:17], 0, s[6:7]
	v_lshl_add_u64 v[52:53], v[22:23], 0, s[6:7]
	v_lshl_add_u64 v[54:55], v[30:31], 0, s[6:7]
	v_lshl_add_u64 v[56:57], v[28:29], 0, s[6:7]
	v_lshl_add_u64 v[58:59], v[26:27], 0, s[6:7]
	v_lshl_add_u64 v[60:61], v[24:25], 0, s[6:7]
	v_lshl_add_u64 v[62:63], v[20:21], 0, s[6:7]
	v_lshl_add_u64 v[64:65], v[18:19], 0, s[6:7]
	global_load_dword v116, v[50:51], off nt
	global_load_dword v117, v[52:53], off nt
	global_load_dword v118, v[54:55], off nt
	global_load_dword v119, v[56:57], off nt
	global_load_dword v120, v[58:59], off nt
	global_load_dword v121, v[60:61], off nt
	global_load_dword v122, v[62:63], off nt
	global_load_dword v123, v[64:65], off nt
	s_add_u32 s6, s6, 0xf2800
	s_addc_u32 s7, s7, 0
	v_lshl_add_u64 v[50:51], v[16:17], 0, s[6:7]
	v_lshl_add_u64 v[52:53], v[22:23], 0, s[6:7]
	v_lshl_add_u64 v[54:55], v[30:31], 0, s[6:7]
	v_lshl_add_u64 v[56:57], v[28:29], 0, s[6:7]
	v_lshl_add_u64 v[58:59], v[26:27], 0, s[6:7]
	v_lshl_add_u64 v[60:61], v[24:25], 0, s[6:7]
	v_lshl_add_u64 v[62:63], v[20:21], 0, s[6:7]
	v_lshl_add_u64 v[64:65], v[18:19], 0, s[6:7]
	global_load_dword v124, v[50:51], off nt
	global_load_dword v125, v[52:53], off nt
	global_load_dword v126, v[54:55], off nt
	global_load_dword v127, v[56:57], off nt
	global_load_dword v128, v[58:59], off nt
	global_load_dword v129, v[60:61], off nt
	global_load_dword v130, v[62:63], off nt
	global_load_dword v131, v[64:65], off nt
	s_add_u32 s6, s6, 0xf2800
	s_addc_u32 s7, s7, 0
	v_lshl_add_u64 v[50:51], v[16:17], 0, s[6:7]
	v_lshl_add_u64 v[52:53], v[22:23], 0, s[6:7]
	v_lshl_add_u64 v[54:55], v[30:31], 0, s[6:7]
	v_lshl_add_u64 v[56:57], v[28:29], 0, s[6:7]
	v_lshl_add_u64 v[58:59], v[26:27], 0, s[6:7]
	v_lshl_add_u64 v[60:61], v[24:25], 0, s[6:7]
	v_lshl_add_u64 v[62:63], v[20:21], 0, s[6:7]
	v_lshl_add_u64 v[64:65], v[18:19], 0, s[6:7]
	global_load_dword v132, v[50:51], off nt
	global_load_dword v133, v[52:53], off nt
	global_load_dword v134, v[54:55], off nt
	global_load_dword v135, v[56:57], off nt
	global_load_dword v136, v[58:59], off nt
	global_load_dword v137, v[60:61], off nt
	global_load_dword v138, v[62:63], off nt
	global_load_dword v139, v[64:65], off nt
	s_add_u32 s6, s6, 0xf2800
	s_addc_u32 s7, s7, 0
	v_mov_b32_e32 v140, v39
	v_add_u32_e32 v141, 0x400, v140
	s_waitcnt vmcnt(30)
	ds_write2_b32 v140, v108, v109 offset1:66
	s_waitcnt vmcnt(28)
	ds_write2_b32 v140, v110, v111 offset0:132 offset1:198
	s_waitcnt vmcnt(26)
	ds_write2_b32 v141, v112, v113 offset0:8 offset1:74
	s_waitcnt vmcnt(24)
	ds_write2_b32 v141, v114, v115 offset0:140 offset1:206
	v_add_u32_e32 v140, 0x840, v39
	v_add_u32_e32 v141, 0x400, v140
	s_waitcnt vmcnt(22)
	ds_write2_b32 v140, v116, v117 offset1:66
	s_waitcnt vmcnt(20)
	ds_write2_b32 v140, v118, v119 offset0:132 offset1:198
	s_waitcnt vmcnt(18)
	ds_write2_b32 v141, v120, v121 offset0:8 offset1:74
	s_waitcnt vmcnt(16)
	ds_write2_b32 v141, v122, v123 offset0:140 offset1:206
	v_add_u32_e32 v140, 0x1080, v39
	v_add_u32_e32 v141, 0x400, v140
	s_waitcnt vmcnt(14)
	ds_write2_b32 v140, v124, v125 offset1:66
	s_waitcnt vmcnt(12)
	ds_write2_b32 v140, v126, v127 offset0:132 offset1:198
	s_waitcnt vmcnt(10)
	ds_write2_b32 v141, v128, v129 offset0:8 offset1:74
	s_waitcnt vmcnt(8)
	ds_write2_b32 v141, v130, v131 offset0:140 offset1:206
	v_add_u32_e32 v140, 0x18c0, v39
	v_add_u32_e32 v141, 0x400, v140
	s_waitcnt vmcnt(6)
	ds_write2_b32 v140, v132, v133 offset1:66
	s_waitcnt vmcnt(4)
	ds_write2_b32 v140, v134, v135 offset0:132 offset1:198
	s_waitcnt vmcnt(2)
	ds_write2_b32 v141, v136, v137 offset0:8 offset1:74
	s_waitcnt vmcnt(0)
	ds_write2_b32 v141, v138, v139 offset0:140 offset1:206
	s_waitcnt lgkmcnt(0)
	ds_read2_b32 v[16:17], v34 offset1:8
	ds_read2_b32 v[18:19], v34 offset0:33 offset1:41
	ds_read2_b32 v[20:21], v34 offset0:66 offset1:74
	ds_read2_b32 v[22:23], v34 offset0:99 offset1:107
	v_mov_b32_e32 v26, v1
	s_waitcnt lgkmcnt(3)
	v_mul_f32_e32 v0, 0x43800000, v16
	s_waitcnt lgkmcnt(2)
	v_mul_f32_e32 v16, 0x43800000, v18
	v_med3_f32 v0, v0, s15, v48
	v_med3_f32 v16, v16, s15, v48
	v_cvt_pk_fp8_f32 v26, v0, v16
	ds_read2_b32 v[28:29], v34 offset0:132 offset1:140
	ds_read2_b32 v[30:31], v34 offset0:165 offset1:173
	ds_read2_b32 v[50:51], v34 offset0:198 offset1:206
	s_waitcnt lgkmcnt(4)
	v_mul_f32_e32 v18, 0x43800000, v20
	s_waitcnt lgkmcnt(3)
	v_mul_f32_e32 v20, 0x43800000, v22
	v_med3_f32 v0, v18, s15, v48
	v_med3_f32 v16, v20, s15, v48
	ds_read2_b32 v[52:53], v34 offset0:231 offset1:239
	v_cvt_pk_fp8_f32 v26, v0, v16 op_sel:[0,0,1]
	s_waitcnt lgkmcnt(3)
	v_mul_f32_e32 v0, 0x43800000, v28
	s_waitcnt lgkmcnt(2)
	v_mul_f32_e32 v16, 0x43800000, v30
	v_med3_f32 v0, v0, s15, v48
	v_med3_f32 v16, v16, s15, v48
	v_mov_b32_e32 v27, v1
	v_cvt_pk_fp8_f32 v27, v0, v16
	s_waitcnt lgkmcnt(1)
	v_mul_f32_e32 v18, 0x43800000, v50
	s_waitcnt lgkmcnt(0)
	v_mul_f32_e32 v0, 0x43800000, v52
	v_med3_f32 v16, v18, s15, v48
	v_med3_f32 v0, v0, s15, v48
	s_mov_b32 s11, s5
	v_cvt_pk_fp8_f32 v27, v16, v0 op_sel:[0,0,1]
	v_or_b32_e32 v0, s23, v33
	v_lshl_add_u64 v[24:25], v[12:13], 0, s[10:11]
	v_lshlrev_b32_e32 v0, 12, v0
	v_lshl_add_u64 v[54:55], v[24:25], 0, v[0:1]
	v_mul_f32_e32 v0, 0x43800000, v17
	v_mul_f32_e32 v16, 0x43800000, v19
	v_med3_f32 v0, v0, s15, v48
	v_med3_f32 v18, v16, s15, v48
	v_mov_b32_e32 v16, v1
	v_cvt_pk_fp8_f32 v16, v0, v18
	v_mul_f32_e32 v17, 0x43800000, v21
	v_mul_f32_e32 v0, 0x43800000, v23
	v_med3_f32 v17, v17, s15, v48
	v_med3_f32 v0, v0, s15, v48
	v_cvt_pk_fp8_f32 v16, v17, v0 op_sel:[0,0,1]
	v_mul_f32_e32 v0, 0x43800000, v29
	v_mul_f32_e32 v17, 0x43800000, v31
	v_med3_f32 v0, v0, s15, v48
	v_med3_f32 v19, v17, s15, v48
	v_mov_b32_e32 v17, v1
	v_cvt_pk_fp8_f32 v17, v0, v19
	v_mul_f32_e32 v18, 0x43800000, v51
	v_mul_f32_e32 v0, 0x43800000, v53
	v_med3_f32 v18, v18, s15, v48
	v_med3_f32 v0, v0, s15, v48
	global_store_dwordx2 v[54:55], v[26:27], off
	v_cvt_pk_fp8_f32 v17, v18, v0 op_sel:[0,0,1]
	v_or_b32_e32 v0, s23, v35
	ds_read2_b32 v[20:21], v34 offset0:16 offset1:24
	ds_read2_b32 v[22:23], v34 offset0:49 offset1:57
	ds_read2_b32 v[26:27], v34 offset0:82 offset1:90
	ds_read2_b32 v[28:29], v34 offset0:115 offset1:123
	v_lshlrev_b32_e32 v0, 12, v0
	v_lshl_add_u64 v[18:19], v[24:25], 0, v[0:1]
	global_store_dwordx2 v[18:19], v[16:17], off
	s_waitcnt lgkmcnt(3)
	v_mul_f32_e32 v0, 0x43800000, v20
	s_waitcnt lgkmcnt(2)
	v_mul_f32_e32 v16, 0x43800000, v22
	v_med3_f32 v0, v0, s15, v48
	v_med3_f32 v18, v16, s15, v48
	v_mov_b32_e32 v16, v1
	v_cvt_pk_fp8_f32 v16, v0, v18
	ds_read2_b32 v[18:19], v34 offset0:148 offset1:156
	ds_read2_b32 v[30:31], v34 offset0:181 offset1:189
	ds_read2_b32 v[50:51], v34 offset0:214 offset1:222
	s_waitcnt lgkmcnt(4)
	v_mul_f32_e32 v17, 0x43800000, v26
	s_waitcnt lgkmcnt(3)
	v_mul_f32_e32 v20, 0x43800000, v28
	v_med3_f32 v0, v17, s15, v48
	v_med3_f32 v17, v20, s15, v48
	ds_read2_b32 v[52:53], v34 offset0:247 offset1:255
	v_cvt_pk_fp8_f32 v16, v0, v17 op_sel:[0,0,1]
	s_waitcnt lgkmcnt(3)
	v_mul_f32_e32 v0, 0x43800000, v18
	s_waitcnt lgkmcnt(2)
	v_mul_f32_e32 v17, 0x43800000, v30
	v_med3_f32 v0, v0, s15, v48
	v_med3_f32 v20, v17, s15, v48
	v_mov_b32_e32 v17, v1
	v_cvt_pk_fp8_f32 v17, v0, v20
	s_waitcnt lgkmcnt(1)
	v_mul_f32_e32 v18, 0x43800000, v50
	s_waitcnt lgkmcnt(0)
	v_mul_f32_e32 v0, 0x43800000, v52
	v_med3_f32 v18, v18, s15, v48
	v_med3_f32 v0, v0, s15, v48
	v_cvt_pk_fp8_f32 v17, v18, v0 op_sel:[0,0,1]
	v_or_b32_e32 v0, s23, v36
	v_lshlrev_b32_e32 v0, 12, v0
	v_lshl_add_u64 v[54:55], v[24:25], 0, v[0:1]
	global_store_dwordx2 v[54:55], v[16:17], off
	v_mul_f32_e32 v0, 0x43800000, v21
	v_mul_f32_e32 v16, 0x43800000, v23
	v_med3_f32 v0, v0, s15, v48
	v_med3_f32 v18, v16, s15, v48
	v_mov_b32_e32 v16, v1
	v_cvt_pk_fp8_f32 v16, v0, v18
	v_mul_f32_e32 v17, 0x43800000, v27
	v_mul_f32_e32 v0, 0x43800000, v29
	v_med3_f32 v17, v17, s15, v48
	v_med3_f32 v0, v0, s15, v48
	v_cvt_pk_fp8_f32 v16, v17, v0 op_sel:[0,0,1]
	v_mul_f32_e32 v0, 0x43800000, v19
	v_mul_f32_e32 v17, 0x43800000, v31
	v_med3_f32 v0, v0, s15, v48
	v_med3_f32 v19, v17, s15, v48
	v_mov_b32_e32 v17, v1
	v_cvt_pk_fp8_f32 v17, v0, v19
	v_mul_f32_e32 v18, 0x43800000, v51
	v_mul_f32_e32 v0, 0x43800000, v53
	v_med3_f32 v18, v18, s15, v48
	v_med3_f32 v0, v0, s15, v48
	v_cvt_pk_fp8_f32 v17, v18, v0 op_sel:[0,0,1]
	v_or_b32_e32 v0, s23, v37
	v_lshlrev_b32_e32 v0, 12, v0
	v_lshl_add_u64 v[18:19], v[24:25], 0, v[0:1]
	global_store_dwordx2 v[18:19], v[16:17], off
	s_waitcnt lgkmcnt(0)
